# v27 plus the last duplicated lgkmcnt(0) at an MFMA block head (gathered MoE GEMM loop)
# baseline (speedup 1.0000x reference)
; #define PG8_STAGE(bufoff, gbase, voff) do { _Pragma("unroll") for (int _i = 0; _i < 2; ++_i) \
;         __builtin_amdgcn_global_load_lds((const unsigned*)((const char*)(gbase) + (voff)[_i]), (LAS unsigned*)(lds + (bufoff) + ldsw + _i * 8192), 16, 0, 0); } while (0)
; #define STG_A(bufoff, kb, h, usen) do { if constexpr (GATHER) { unsigned o_[2] = {(usen) ? noff[h][0] : coff[h][0], (usen) ? noff[h][1] : coff[h][1]}; PG8_STAGE(bufoff, (const char*)A + (kb), o_); } \
;         else { PG8_STAGE(bufoff, ((usen) ? nA : cA) + (kb) + (size_t)(h) * hstep, voffA); } } while (0)
; #define PG8_LDA(dst, b, h) do { _Pragma("unroll") for (int m = 0; m < 4; ++m) _Pragma("unroll") for (int k = 0; k < 2; ++k) dst[m][k] = *(const LAS bf16x8*)(lds + PG8_SA(b, h) + aoff + m * 2048 + k * 1024); } while (0)
; #define PG8_LDB(dst, b, h) do { _Pragma("unroll") for (int n = 0; n < 2; ++n) _Pragma("unroll") for (int k = 0; k < 2; ++k) dst[n][k] = *(const LAS bf16x8*)(lds + PG8_SB(b, h) + boff + n * 2048 + k * 1024); } while (0)
; #define PG8_WAIT_L(n) asm volatile("s_waitcnt lgkmcnt(" #n ")" ::: "memory")
; #define PG8_BAR __builtin_amdgcn_s_barrier()
; #define PG8_SCHED __builtin_amdgcn_sched_barrier(0)
; template <class Epi, bool GATHER = false>
; __device__ __forceinline__ void gemm_phase(LAS unsigned char* lds, const bf16_t* A, const bf16_t* Bt, const int K_, const Sched& S, const Epi& E, const int* gidx = nullptr) {
;     ...
;         for (int t = 0; t < nt; t += 2) {
;             const bool last = (t == nt - 2);
;             const size_t k1 = (size_t)(t + 1) * kstep, k2 = last ? (size_t)0 : (size_t)(t + 2) * kstep, k3 = k2 + kstep;
;             const char* b2 = last ? nB : cB + (size_t)(t + 2) * kstep;
;             const char* b3 = b2 + kstep;
;             PG8_LDB(B0, 0, 0); PG8_SCHED; PG8_LDA(At, 0, 0); STG_A(PG8_SA(1, 1), k1, 1, false);
;             PG8_WAIT_L(8); PG8_BAR; PG8_WAIT_L(0); PG8_MMA(0, 0, At, B0); PG8_BAR; PG8_SCHED;
;             PG8_LDB(B1, 0, 1); PG8_STAGE(PG8_SB(0, 0), b2, voffA);
;             PG8_BAR; PG8_WAIT_L(0); PG8_MMA(0, 1, At, B1); PG8_BAR;
;             PG8_LDA(At, 0, 1); STG_A(PG8_SA(0, 0), k2, 0, last);
;             PG8_BAR; PG8_WAIT_L(0); PG8_MMA(1, 0, At, B0); PG8_BAR; PG8_SCHED;
.LBB0_1496:
	s_cmp_eq_u32 s43, s50
	s_cselect_b64 vcc, -1, 0
	s_add_i32 s50, s50, 2
	s_add_u32 s31, s16, s4
	s_addc_u32 s33, s17, s5
	s_and_b64 s[20:21], vcc, exec
	s_cselect_b32 s21, s15, s33
	s_cselect_b32 s20, s14, s31
	s_add_i32 s31, 0, 0x10000
	v_add_u32_e32 v112, s31, v156
	ds_read_b128 v[158:161], v112
	ds_read_b128 v[162:165], v112 offset:1024
	ds_read_b128 v[166:169], v112 offset:2048
	ds_read_b128 v[188:191], v112 offset:3072
	s_and_b64 s[52:53], vcc, exec
	s_cselect_b32 s33, 0, s5
	s_cselect_b32 s51, 0, s4
	v_lshl_add_u64 v[224:225], s[18:19], 0, v[152:153]
	s_add_i32 m0, s37, 0xc000
	ds_read_b128 v[192:195], v157
	ds_read_b128 v[196:199], v157 offset:1024
	ds_read_b128 v[200:203], v157 offset:2048
	ds_read_b128 v[204:207], v157 offset:3072
	ds_read_b128 v[208:211], v157 offset:4096
	ds_read_b128 v[212:215], v157 offset:5120
	ds_read_b128 v[216:219], v157 offset:6144
	ds_read_b128 v[220:223], v157 offset:7168
	global_load_lds_dwordx4 v[224:225], off
	v_lshl_add_u64 v[224:225], s[18:19], 0, v[154:155]
	s_add_i32 m0, s37, 0xe000
	s_nop 0
	global_load_lds_dwordx4 v[224:225], off
	s_waitcnt lgkmcnt(8)
	s_barrier
	s_waitcnt lgkmcnt(0)
	s_setprio 1
	v_mfma_f32_16x16x32_bf16 v[126:129], v[158:161], v[192:195], v[126:129]
	v_mfma_f32_16x16x32_bf16 v[118:121], v[166:169], v[192:195], v[118:121]
	v_mfma_f32_16x16x32_bf16 v[108:111], v[158:161], v[200:203], v[108:111]
	v_mfma_f32_16x16x32_bf16 v[100:103], v[166:169], v[200:203], v[100:103]
	v_mfma_f32_16x16x32_bf16 v[92:95], v[158:161], v[208:211], v[92:95]
	v_mfma_f32_16x16x32_bf16 v[84:87], v[166:169], v[208:211], v[84:87]
	v_mfma_f32_16x16x32_bf16 v[76:79], v[158:161], v[216:219], v[76:79]
	v_mfma_f32_16x16x32_bf16 v[68:71], v[166:169], v[216:219], v[68:71]
	v_mfma_f32_16x16x32_bf16 v[126:129], v[162:165], v[196:199], v[126:129]
	v_mfma_f32_16x16x32_bf16 v[118:121], v[188:191], v[196:199], v[118:121]
	v_mfma_f32_16x16x32_bf16 v[108:111], v[162:165], v[204:207], v[108:111]
	v_mfma_f32_16x16x32_bf16 v[100:103], v[188:191], v[204:207], v[100:103]
	v_mfma_f32_16x16x32_bf16 v[92:95], v[162:165], v[212:215], v[92:95]
	v_mfma_f32_16x16x32_bf16 v[84:87], v[188:191], v[212:215], v[84:87]
	v_mfma_f32_16x16x32_bf16 v[76:79], v[162:165], v[220:223], v[76:79]
	v_mfma_f32_16x16x32_bf16 v[68:71], v[188:191], v[220:223], v[68:71]
	s_setprio 0
	s_barrier
	s_add_i32 s54, 0, 0x14000
	s_add_i32 s31, s31, s35
	v_add_u32_e32 v112, s54, v156
	v_lshl_add_u64 v[240:241], s[20:21], 0, v[132:133]
	s_mov_b32 m0, s31
	ds_read_b128 v[224:227], v112
	ds_read_b128 v[228:231], v112 offset:1024
	ds_read_b128 v[232:235], v112 offset:2048
	ds_read_b128 v[236:239], v112 offset:3072
	global_load_lds_dwordx4 v[240:241], off
	v_lshl_add_u64 v[242:243], s[20:21], 0, v[136:137]
	s_add_i32 m0, s31, 0x2000
	s_nop 0
	global_load_lds_dwordx4 v[242:243], off
	s_barrier
	s_waitcnt lgkmcnt(0)
	s_setprio 1
	v_mfma_f32_16x16x32_bf16 v[122:125], v[224:227], v[192:195], v[122:125]
	v_mfma_f32_16x16x32_bf16 v[114:117], v[232:235], v[192:195], v[114:117]
	v_mfma_f32_16x16x32_bf16 v[104:107], v[224:227], v[200:203], v[104:107]
	v_mfma_f32_16x16x32_bf16 v[96:99], v[232:235], v[200:203], v[96:99]
	v_mfma_f32_16x16x32_bf16 v[88:91], v[224:227], v[208:211], v[88:91]
	v_mfma_f32_16x16x32_bf16 v[80:83], v[232:235], v[208:211], v[80:83]
	v_mfma_f32_16x16x32_bf16 v[72:75], v[224:227], v[216:219], v[72:75]
	v_mfma_f32_16x16x32_bf16 v[64:67], v[232:235], v[216:219], v[64:67]
	v_mfma_f32_16x16x32_bf16 v[122:125], v[228:231], v[196:199], v[122:125]
	v_mfma_f32_16x16x32_bf16 v[114:117], v[236:239], v[196:199], v[114:117]
	v_mfma_f32_16x16x32_bf16 v[104:107], v[228:231], v[204:207], v[104:107]
	v_mfma_f32_16x16x32_bf16 v[96:99], v[236:239], v[204:207], v[96:99]
	v_mfma_f32_16x16x32_bf16 v[88:91], v[228:231], v[212:215], v[88:91]
	v_mfma_f32_16x16x32_bf16 v[80:83], v[236:239], v[212:215], v[80:83]
	v_mfma_f32_16x16x32_bf16 v[72:75], v[228:231], v[220:223], v[72:75]
	v_mfma_f32_16x16x32_bf16 v[64:67], v[236:239], v[220:223], v[64:67]
	s_setprio 0
	s_add_u32 s52, s56, s51
	s_mov_b32 m0, s37
	v_cndmask_b32_e32 v112, v148, v140, vcc
	s_addc_u32 s53, s57, s33
	s_barrier
	ds_read_b128 v[192:195], v157 offset:16384
	ds_read_b128 v[196:199], v157 offset:17408
	ds_read_b128 v[200:203], v157 offset:18432
	ds_read_b128 v[204:207], v157 offset:19456
	ds_read_b128 v[208:211], v157 offset:20480
	ds_read_b128 v[212:215], v157 offset:21504
	ds_read_b128 v[216:219], v157 offset:22528
	ds_read_b128 v[220:223], v157 offset:23552
	v_cndmask_b32_e32 v244, v150, v142, vcc
	global_load_lds_dwordx4 v112, s[52:53]
	s_mov_b32 m0, s38
	v_mov_b32_e32 v245, v113
	global_load_lds_dwordx4 v244, s[52:53]
	s_barrier
	s_waitcnt lgkmcnt(0)
	v_lshl_add_u64 v[246:247], s[52:53], 0, v[112:113]
	v_lshl_add_u64 v[244:245], s[52:53], 0, v[244:245]
	s_setprio 1
	v_mfma_f32_16x16x32_bf16 v[60:63], v[158:161], v[192:195], v[60:63]
	v_mfma_f32_16x16x32_bf16 v[52:55], v[166:169], v[192:195], v[52:55]
	v_mfma_f32_16x16x32_bf16 v[44:47], v[158:161], v[200:203], v[44:47]
	v_mfma_f32_16x16x32_bf16 v[36:39], v[166:169], v[200:203], v[36:39]
	v_mfma_f32_16x16x32_bf16 v[28:31], v[158:161], v[208:211], v[28:31]
	v_mfma_f32_16x16x32_bf16 v[20:23], v[166:169], v[208:211], v[20:23]
	v_mfma_f32_16x16x32_bf16 v[12:15], v[158:161], v[216:219], v[12:15]
	v_mfma_f32_16x16x32_bf16 v[4:7], v[166:169], v[216:219], v[4:7]
	v_mfma_f32_16x16x32_bf16 v[60:63], v[162:165], v[196:199], v[60:63]
	v_mfma_f32_16x16x32_bf16 v[52:55], v[188:191], v[196:199], v[52:55]
	v_mfma_f32_16x16x32_bf16 v[44:47], v[162:165], v[204:207], v[44:47]
	v_mfma_f32_16x16x32_bf16 v[36:39], v[188:191], v[204:207], v[36:39]
	v_mfma_f32_16x16x32_bf16 v[28:31], v[162:165], v[212:215], v[28:31]
	v_mfma_f32_16x16x32_bf16 v[20:23], v[188:191], v[212:215], v[20:23]
	v_mfma_f32_16x16x32_bf16 v[12:15], v[162:165], v[220:223], v[12:15]
	v_mfma_f32_16x16x32_bf16 v[4:7], v[188:191], v[220:223], v[4:7]
	s_setprio 0
	s_barrier
; #define PG8_STAGE(bufoff, gbase, voff) do { _Pragma("unroll") for (int _i = 0; _i < 2; ++_i) \
;         __builtin_amdgcn_global_load_lds((const unsigned*)((const char*)(gbase) + (voff)[_i]), (LAS unsigned*)(lds + (bufoff) + ldsw + _i * 8192), 16, 0, 0); } while (0)
; #define STG_A(bufoff, kb, h, usen) do { if constexpr (GATHER) { unsigned o_[2] = {(usen) ? noff[h][0] : coff[h][0], (usen) ? noff[h][1] : coff[h][1]}; PG8_STAGE(bufoff, (const char*)A + (kb), o_); } \
;         else { PG8_STAGE(bufoff, ((usen) ? nA : cA) + (kb) + (size_t)(h) * hstep, voffA); } } while (0)
; #define PG8_LDA(dst, b, h) do { _Pragma("unroll") for (int m = 0; m < 4; ++m) _Pragma("unroll") for (int k = 0; k < 2; ++k) dst[m][k] = *(const LAS bf16x8*)(lds + PG8_SA(b, h) + aoff + m * 2048 + k * 1024); } while (0)
; #define PG8_LDB(dst, b, h) do { _Pragma("unroll") for (int n = 0; n < 2; ++n) _Pragma("unroll") for (int k = 0; k < 2; ++k) dst[n][k] = *(const LAS bf16x8*)(lds + PG8_SB(b, h) + boff + n * 2048 + k * 1024); } while (0)
; #define PG8_MMA(ai, bj, At, Bt_) do { __builtin_amdgcn_s_setprio(1); _Pragma("unroll") for (int m = 0; m < 4; ++m) _Pragma("unroll") for (int n = 0; n < 2; ++n) _Pragma("unroll") for (int k = 0; k < 2; ++k) \
;         acc[ai][bj][m][n] = __builtin_amdgcn_mfma_f32_16x16x32_bf16(Bt_[n][k], At[m][k], acc[ai][bj][m][n], 0, 0, 0); __builtin_amdgcn_s_setprio(0); } while (0)
; #define PG8_WAIT_V(n) asm volatile("s_waitcnt vmcnt(" #n ")" ::: "memory")
; template <class Epi, bool GATHER = false>
; __device__ __forceinline__ void gemm_phase(LAS unsigned char* lds, const bf16_t* A, const bf16_t* Bt, const int K_, const Sched& S, const Epi& E, const int* gidx = nullptr) {
;     ...
;             PG8_STAGE(PG8_SB(0, 1), b2 + hstep, voffA);
;             PG8_WAIT_V(6); PG8_BAR; PG8_MMA(1, 1, At, B1); PG8_BAR;
;             PG8_LDB(B0, 1, 0); PG8_SCHED; PG8_LDA(At, 1, 0); STG_A(PG8_SA(0, 1), k2, 1, last);
;             PG8_WAIT_L(8); PG8_BAR; PG8_WAIT_L(0); PG8_MMA(0, 0, At, B0); PG8_BAR; PG8_SCHED;
;             PG8_LDB(B1, 1, 1); PG8_STAGE(PG8_SB(1, 0), b3, voffA);
;             PG8_BAR; PG8_WAIT_L(0); PG8_MMA(0, 1, At, B1); PG8_BAR;
;             PG8_LDA(At, 1, 1); STG_A(PG8_SA(1, 0), k3, 0, last);
;             PG8_BAR; PG8_WAIT_L(0); PG8_MMA(1, 0, At, B0); PG8_BAR; PG8_SCHED;
;             PG8_STAGE(PG8_SB(1, 1), b3 + hstep, voffA);
	s_add_u32 s20, s20, s6
	s_addc_u32 s21, s21, s7
	s_add_i32 s31, s54, s35
	v_lshl_add_u64 v[248:249], s[20:21], 0, v[132:133]
	s_mov_b32 m0, s31
	v_lshl_add_u64 v[250:251], s[20:21], 0, v[136:137]
	global_load_lds_dwordx4 v[248:249], off
	s_add_i32 m0, s31, 0x2000
	s_nop 0
	global_load_lds_dwordx4 v[250:251], off
	s_waitcnt vmcnt(6)
	s_barrier
	s_setprio 1
	v_mfma_f32_16x16x32_bf16 v[56:59], v[224:227], v[192:195], v[56:59]
	v_mfma_f32_16x16x32_bf16 v[48:51], v[232:235], v[192:195], v[48:51]
	v_mfma_f32_16x16x32_bf16 v[40:43], v[224:227], v[200:203], v[40:43]
	v_mfma_f32_16x16x32_bf16 v[32:35], v[232:235], v[200:203], v[32:35]
	v_mfma_f32_16x16x32_bf16 v[24:27], v[224:227], v[208:211], v[24:27]
	v_mfma_f32_16x16x32_bf16 v[16:19], v[232:235], v[208:211], v[16:19]
	v_mfma_f32_16x16x32_bf16 v[8:11], v[224:227], v[216:219], v[8:11]
	v_mfma_f32_16x16x32_bf16 v[0:3], v[232:235], v[216:219], v[0:3]
	v_mfma_f32_16x16x32_bf16 v[56:59], v[228:231], v[196:199], v[56:59]
	v_mfma_f32_16x16x32_bf16 v[48:51], v[236:239], v[196:199], v[48:51]
	v_mfma_f32_16x16x32_bf16 v[40:43], v[228:231], v[204:207], v[40:43]
	v_mfma_f32_16x16x32_bf16 v[32:35], v[236:239], v[204:207], v[32:35]
	v_mfma_f32_16x16x32_bf16 v[24:27], v[228:231], v[212:215], v[24:27]
	v_mfma_f32_16x16x32_bf16 v[16:19], v[236:239], v[212:215], v[16:19]
	v_mfma_f32_16x16x32_bf16 v[8:11], v[228:231], v[220:223], v[8:11]
	v_mfma_f32_16x16x32_bf16 v[0:3], v[236:239], v[220:223], v[0:3]
	s_setprio 0
	s_add_i32 s20, 0, 0x18000
	v_add_u32_e32 v112, s20, v156
	s_barrier
	ds_read_b128 v[158:161], v112
	ds_read_b128 v[162:165], v112 offset:1024
	ds_read_b128 v[166:169], v112 offset:2048
	ds_read_b128 v[188:191], v112 offset:3072
	s_mov_b32 m0, s39
	v_cndmask_b32_e32 v112, v152, v144, vcc
	ds_read_b128 v[192:195], v157 offset:32768
	ds_read_b128 v[196:199], v157 offset:33792
	ds_read_b128 v[200:203], v157 offset:34816
	ds_read_b128 v[204:207], v157 offset:35840
	ds_read_b128 v[208:211], v157 offset:36864
	ds_read_b128 v[212:215], v157 offset:37888
	ds_read_b128 v[216:219], v157 offset:38912
	ds_read_b128 v[220:223], v157 offset:39936
	v_cndmask_b32_e32 v139, v154, v146, vcc
	global_load_lds_dwordx4 v112, s[52:53]
	s_mov_b32 m0, s40
	s_nop 0
	global_load_lds_dwordx4 v139, s[52:53]
	s_waitcnt lgkmcnt(8)
	s_barrier
	s_waitcnt lgkmcnt(0)
	s_setprio 1
	v_mfma_f32_16x16x32_bf16 v[126:129], v[158:161], v[192:195], v[126:129]
	v_mfma_f32_16x16x32_bf16 v[118:121], v[166:169], v[192:195], v[118:121]
	v_mfma_f32_16x16x32_bf16 v[108:111], v[158:161], v[200:203], v[108:111]
	v_mfma_f32_16x16x32_bf16 v[100:103], v[166:169], v[200:203], v[100:103]
	v_mfma_f32_16x16x32_bf16 v[92:95], v[158:161], v[208:211], v[92:95]
	v_mfma_f32_16x16x32_bf16 v[84:87], v[166:169], v[208:211], v[84:87]
	v_mfma_f32_16x16x32_bf16 v[76:79], v[158:161], v[216:219], v[76:79]
	v_mfma_f32_16x16x32_bf16 v[68:71], v[166:169], v[216:219], v[68:71]
	v_mfma_f32_16x16x32_bf16 v[126:129], v[162:165], v[196:199], v[126:129]
	v_mfma_f32_16x16x32_bf16 v[118:121], v[188:191], v[196:199], v[118:121]
	v_mfma_f32_16x16x32_bf16 v[108:111], v[162:165], v[204:207], v[108:111]
	v_mfma_f32_16x16x32_bf16 v[100:103], v[188:191], v[204:207], v[100:103]
	v_mfma_f32_16x16x32_bf16 v[92:95], v[162:165], v[212:215], v[92:95]
	v_mfma_f32_16x16x32_bf16 v[84:87], v[188:191], v[212:215], v[84:87]
	v_mfma_f32_16x16x32_bf16 v[76:79], v[162:165], v[220:223], v[76:79]
	v_mfma_f32_16x16x32_bf16 v[68:71], v[188:191], v[220:223], v[68:71]
	s_setprio 0
	s_barrier
	s_add_i32 s21, 0, 0x1c000
	s_add_i32 s20, s20, s35
	v_add_u32_e32 v112, s21, v156
	v_lshl_add_u64 v[240:241], v[240:241], 0, s[2:3]
	s_mov_b32 m0, s20
	ds_read_b128 v[224:227], v112
	ds_read_b128 v[228:231], v112 offset:1024
	ds_read_b128 v[232:235], v112 offset:2048
	ds_read_b128 v[236:239], v112 offset:3072
	global_load_lds_dwordx4 v[240:241], off
	v_lshl_add_u64 v[240:241], v[242:243], 0, s[2:3]
	s_add_i32 m0, s20, 0x2000
	s_nop 0
	global_load_lds_dwordx4 v[240:241], off
	s_barrier
; #define PG8_STAGE(bufoff, gbase, voff) do { _Pragma("unroll") for (int _i = 0; _i < 2; ++_i) \
;         __builtin_amdgcn_global_load_lds((const unsigned*)((const char*)(gbase) + (voff)[_i]), (LAS unsigned*)(lds + (bufoff) + ldsw + _i * 8192), 16, 0, 0); } while (0)
; #define STG_A(bufoff, kb, h, usen) do { if constexpr (GATHER) { unsigned o_[2] = {(usen) ? noff[h][0] : coff[h][0], (usen) ? noff[h][1] : coff[h][1]}; PG8_STAGE(bufoff, (const char*)A + (kb), o_); } \
;         else { PG8_STAGE(bufoff, ((usen) ? nA : cA) + (kb) + (size_t)(h) * hstep, voffA); } } while (0)
; #define PG8_LDA(dst, b, h) do { _Pragma("unroll") for (int m = 0; m < 4; ++m) _Pragma("unroll") for (int k = 0; k < 2; ++k) dst[m][k] = *(const LAS bf16x8*)(lds + PG8_SA(b, h) + aoff + m * 2048 + k * 1024); } while (0)
; #define PG8_MMA(ai, bj, At, Bt_) do { __builtin_amdgcn_s_setprio(1); _Pragma("unroll") for (int m = 0; m < 4; ++m) _Pragma("unroll") for (int n = 0; n < 2; ++n) _Pragma("unroll") for (int k = 0; k < 2; ++k) \
;         acc[ai][bj][m][n] = __builtin_amdgcn_mfma_f32_16x16x32_bf16(Bt_[n][k], At[m][k], acc[ai][bj][m][n], 0, 0, 0); __builtin_amdgcn_s_setprio(0); } while (0)
; #define PG8_WAIT_V(n) asm volatile("s_waitcnt vmcnt(" #n ")" ::: "memory")
; #define PG8_WAIT_L(n) asm volatile("s_waitcnt lgkmcnt(" #n ")" ::: "memory")
; #define PG8_BAR __builtin_amdgcn_s_barrier()
; #define PG8_SCHED __builtin_amdgcn_sched_barrier(0)
; template <class Epi, bool GATHER = false>
; __device__ __forceinline__ void gemm_phase(LAS unsigned char* lds, const bf16_t* A, const bf16_t* Bt, const int K_, const Sched& S, const Epi& E, const int* gidx = nullptr) {
;     ...
;             PG8_LDA(At, 1, 1); STG_A(PG8_SA(1, 0), k3, 0, last);
;             PG8_BAR; PG8_WAIT_L(0); PG8_MMA(1, 0, At, B0); PG8_BAR; PG8_SCHED;
;             PG8_STAGE(PG8_SB(1, 1), b3 + hstep, voffA);
;             PG8_WAIT_V(6); PG8_BAR; PG8_MMA(1, 1, At, B1); PG8_BAR;
;         }
;         E(acc, cur, wr, wc, fr, fq);
;         if (!has_next) break;
	s_waitcnt lgkmcnt(0)
	s_setprio 1
	v_mfma_f32_16x16x32_bf16 v[122:125], v[224:227], v[192:195], v[122:125]
	v_mfma_f32_16x16x32_bf16 v[114:117], v[232:235], v[192:195], v[114:117]
	v_mfma_f32_16x16x32_bf16 v[104:107], v[224:227], v[200:203], v[104:107]
	v_mfma_f32_16x16x32_bf16 v[96:99], v[232:235], v[200:203], v[96:99]
	v_mfma_f32_16x16x32_bf16 v[88:91], v[224:227], v[208:211], v[88:91]
	v_mfma_f32_16x16x32_bf16 v[80:83], v[232:235], v[208:211], v[80:83]
	v_mfma_f32_16x16x32_bf16 v[72:75], v[224:227], v[216:219], v[72:75]
	v_mfma_f32_16x16x32_bf16 v[64:67], v[232:235], v[216:219], v[64:67]
	v_mfma_f32_16x16x32_bf16 v[122:125], v[228:231], v[196:199], v[122:125]
	v_mfma_f32_16x16x32_bf16 v[114:117], v[236:239], v[196:199], v[114:117]
	v_mfma_f32_16x16x32_bf16 v[104:107], v[228:231], v[204:207], v[104:107]
	v_mfma_f32_16x16x32_bf16 v[96:99], v[236:239], v[204:207], v[96:99]
	v_mfma_f32_16x16x32_bf16 v[88:91], v[228:231], v[212:215], v[88:91]
	v_mfma_f32_16x16x32_bf16 v[80:83], v[236:239], v[212:215], v[80:83]
	v_mfma_f32_16x16x32_bf16 v[72:75], v[228:231], v[220:223], v[72:75]
	v_mfma_f32_16x16x32_bf16 v[64:67], v[236:239], v[220:223], v[64:67]
	s_setprio 0
	s_mov_b32 m0, s41
	v_lshl_add_u64 v[240:241], v[246:247], 0, s[2:3]
	s_barrier
	ds_read_b128 v[192:195], v157 offset:49152
	ds_read_b128 v[196:199], v157 offset:50176
	ds_read_b128 v[200:203], v157 offset:51200
	ds_read_b128 v[204:207], v157 offset:52224
	ds_read_b128 v[208:211], v157 offset:53248
	ds_read_b128 v[212:215], v157 offset:54272
	ds_read_b128 v[216:219], v157 offset:55296
	ds_read_b128 v[220:223], v157 offset:56320
	global_load_lds_dwordx4 v[240:241], off
	v_lshl_add_u64 v[240:241], v[244:245], 0, s[2:3]
	s_mov_b32 m0, s42
	s_nop 0
	global_load_lds_dwordx4 v[240:241], off
	s_barrier
	s_waitcnt lgkmcnt(0)
	s_setprio 1
	v_mfma_f32_16x16x32_bf16 v[60:63], v[158:161], v[192:195], v[60:63]
	v_mfma_f32_16x16x32_bf16 v[52:55], v[166:169], v[192:195], v[52:55]
	v_mfma_f32_16x16x32_bf16 v[44:47], v[158:161], v[200:203], v[44:47]
	v_mfma_f32_16x16x32_bf16 v[36:39], v[166:169], v[200:203], v[36:39]
	v_mfma_f32_16x16x32_bf16 v[28:31], v[158:161], v[208:211], v[28:31]
	v_mfma_f32_16x16x32_bf16 v[20:23], v[166:169], v[208:211], v[20:23]
	v_mfma_f32_16x16x32_bf16 v[12:15], v[158:161], v[216:219], v[12:15]
	v_mfma_f32_16x16x32_bf16 v[4:7], v[166:169], v[216:219], v[4:7]
	v_mfma_f32_16x16x32_bf16 v[60:63], v[162:165], v[196:199], v[60:63]
	v_mfma_f32_16x16x32_bf16 v[52:55], v[188:191], v[196:199], v[52:55]
	v_mfma_f32_16x16x32_bf16 v[44:47], v[162:165], v[204:207], v[44:47]
	v_mfma_f32_16x16x32_bf16 v[36:39], v[188:191], v[204:207], v[36:39]
	v_mfma_f32_16x16x32_bf16 v[28:31], v[162:165], v[212:215], v[28:31]
	v_mfma_f32_16x16x32_bf16 v[20:23], v[188:191], v[212:215], v[20:23]
	v_mfma_f32_16x16x32_bf16 v[12:15], v[162:165], v[220:223], v[12:15]
	v_mfma_f32_16x16x32_bf16 v[4:7], v[188:191], v[220:223], v[4:7]
	s_setprio 0
	s_barrier
	s_add_i32 s20, s21, s35
	v_lshl_add_u64 v[158:159], v[248:249], 0, s[2:3]
	s_mov_b32 m0, s20
	s_nop 0
	global_load_lds_dwordx4 v[158:159], off
	v_lshl_add_u64 v[158:159], v[250:251], 0, s[2:3]
	s_add_i32 m0, s20, 0x2000
	s_nop 0
	global_load_lds_dwordx4 v[158:159], off
	s_waitcnt vmcnt(6)
	s_barrier
	s_setprio 1
	v_mfma_f32_16x16x32_bf16 v[56:59], v[224:227], v[192:195], v[56:59]
	v_mfma_f32_16x16x32_bf16 v[48:51], v[232:235], v[192:195], v[48:51]
	v_mfma_f32_16x16x32_bf16 v[40:43], v[224:227], v[200:203], v[40:43]
	v_mfma_f32_16x16x32_bf16 v[32:35], v[232:235], v[200:203], v[32:35]
	v_mfma_f32_16x16x32_bf16 v[24:27], v[224:227], v[208:211], v[24:27]
	v_mfma_f32_16x16x32_bf16 v[16:19], v[232:235], v[208:211], v[16:19]
	v_mfma_f32_16x16x32_bf16 v[8:11], v[224:227], v[216:219], v[8:11]
	v_mfma_f32_16x16x32_bf16 v[0:3], v[232:235], v[216:219], v[0:3]
	v_mfma_f32_16x16x32_bf16 v[56:59], v[228:231], v[196:199], v[56:59]
	v_mfma_f32_16x16x32_bf16 v[48:51], v[236:239], v[196:199], v[48:51]
	v_mfma_f32_16x16x32_bf16 v[40:43], v[228:231], v[204:207], v[40:43]
	v_mfma_f32_16x16x32_bf16 v[32:35], v[236:239], v[204:207], v[32:35]
	v_mfma_f32_16x16x32_bf16 v[24:27], v[228:231], v[212:215], v[24:27]
	v_mfma_f32_16x16x32_bf16 v[16:19], v[236:239], v[212:215], v[16:19]
	v_mfma_f32_16x16x32_bf16 v[8:11], v[228:231], v[220:223], v[8:11]
	v_mfma_f32_16x16x32_bf16 v[0:3], v[236:239], v[220:223], v[0:3]
	s_setprio 0
	s_add_u32 s4, s4, 0x100
	s_addc_u32 s5, s5, 0
	s_add_u32 s18, s18, 0x100
	s_addc_u32 s19, s19, 0
	s_cmp_ge_i32 s50, s1
	s_barrier
	s_cbranch_scc0 .LBB0_1496
	v_readlane_b32 s50, v255, 32
	s_mov_b64 s[20:21], s[58:59]
	v_readlane_b32 s51, v255, 33
	v_readlane_b32 s52, v255, 34
	v_readlane_b32 s53, v255, 35
	s_branch .LBB0_1487
